# mix1a: dynamic tile scheduling with longest-first order (poolc window 16, 8, 4, 2, then kvstate), next index grabbed from an atomic counter one tile ahead
# baseline (speedup 1.0000x reference)
.LBB0_500:
	s_or_b64 exec, exec, s[0:1]
	s_cmpk_gt_i32 s2, 0x7ff
	s_waitcnt lgkmcnt(0)
	s_barrier
	s_cbranch_scc1 .LBB0_515
	v_xor_b32_e32 v1, v128, v131
	v_lshlrev_b32_e32 v1, 3, v1
	s_movk_i32 s1, 0x1e0
	v_and_b32_e32 v2, 56, v1
	v_and_b32_e32 v1, 0x60, v158
	v_and_or_b32 v4, v153, s1, v138
	v_bitop3_b32 v6, v128, v139, 3 bitop3:0x6c
	s_movk_i32 s0, 0x60
	v_lshlrev_b32_e32 v7, 4, v6
	v_lshlrev_b32_e32 v9, 7, v4
	v_lshlrev_b32_e32 v4, 7, v1
	v_and_b32_e32 v6, 0x1f0, v153
	s_movk_i32 s1, 0x50
	v_bitop3_b32 v24, v4, v6, s0 bitop3:0xf6
	s_movk_i32 s0, 0x70
	v_or_b32_e32 v13, v4, v6
	v_bitop3_b32 v15, v4, v6, 16 bitop3:0xf6
	v_bitop3_b32 v17, v4, v6, 32 bitop3:0xf6
	v_bitop3_b32 v19, v4, v6, 48 bitop3:0xf6
	v_bitop3_b32 v22, v4, v6, 64 bitop3:0xf6
	v_bitop3_b32 v23, v4, v6, s1 bitop3:0xf6
	v_bitop3_b32 v25, v4, v6, s0 bitop3:0xf6
	v_lshlrev_b32_e32 v10, 13, v135
	v_lshl_add_u32 v4, v134, 3, v138
	v_lshlrev_b32_e32 v8, 5, v138
	v_or3_b32 v67, v10, v137, v8
	v_add_u32_e32 v8, 0x60, v4
	v_lshl_or_b32 v6, v134, 11, v10
	v_and_b32_e32 v8, 0x7f, v8
	v_lshl_or_b32 v148, v4, 2, v6
	v_lshl_or_b32 v149, v8, 2, v6
	v_add_u32_e32 v4, 0x70, v4
	v_add_u32_e32 v8, 8, v133
	v_lshlrev_b32_e32 v12, 5, v135
	v_and_b32_e32 v4, 0x7f, v4
	v_and_b32_e32 v8, 0x78, v8
	v_mov_b32_e32 v65, 0
	v_lshl_or_b32 v150, v4, 2, v6
	v_or_b32_e32 v20, v134, v12
	v_lshlrev_b32_e32 v6, 9, v136
	v_lshlrev_b32_e32 v8, 2, v8
	v_or_b32_e32 v21, v136, v12
	v_add_u32_e32 v14, 16, v133
	v_lshlrev_b32_e32 v64, 1, v1
	v_lshlrev_b32_e32 v4, 7, v20
	v_or3_b32 v151, v10, v6, v8
	v_lshlrev_b32_e32 v6, 7, v21
	v_and_b32_e32 v14, 0x78, v14
	v_add_u32_e32 v16, 24, v133
	v_lshlrev_b32_e32 v68, 12, v20
	v_lshlrev_b32_e32 v70, 12, v21
	v_lshl_add_u64 v[20:21], s[50:51], 0, v[64:65]
	s_mov_b64 s[0:1], 0xba00000
	v_lshlrev_b32_e32 v64, 9, v157
	v_lshlrev_b32_e32 v8, 9, v132
	v_lshlrev_b32_e32 v14, 2, v14
	v_and_b32_e32 v16, 0x78, v16
	v_or_b32_e32 v18, 16, v12
	v_lshl_add_u64 v[84:85], v[20:21], 0, s[0:1]
	v_lshl_add_u64 v[20:21], s[50:51], 0, v[64:65]
	v_lshlrev_b32_e32 v64, 1, v2
	v_or3_b32 v160, v10, v8, v14
	v_or_b32_e32 v26, v132, v12
	v_lshlrev_b32_e32 v14, 9, v130
	v_lshlrev_b32_e32 v16, 2, v16
	v_or_b32_e32 v27, v130, v12
	v_or_b32_e32 v28, v18, v134
	v_or_b32_e32 v29, v136, v18
	v_or_b32_e32 v30, v132, v18
	v_or_b32_e32 v31, v130, v18
	v_lshl_add_u64 v[20:21], v[20:21], 0, v[64:65]
	s_mov_b64 s[0:1], 0x1000000
	v_and_b32_e32 v0, 0x7f000, v156
	v_and_b32_e32 v3, 14, v153
	v_lshlrev_b32_e32 v5, 7, v138
	v_lshlrev_b32_e32 v11, 4, v152
	v_lshlrev_b32_e32 v8, 7, v26
	v_or3_b32 v161, v10, v14, v16
	v_lshlrev_b32_e32 v10, 7, v27
	v_lshlrev_b32_e32 v12, 7, v28
	v_lshlrev_b32_e32 v14, 7, v29
	v_lshlrev_b32_e32 v16, 7, v30
	v_lshlrev_b32_e32 v18, 7, v31
	s_add_u32 s33, s50, 0x3a00000
	v_lshl_add_u64 v[86:87], v[20:21], 0, s[0:1]
	v_lshl_add_u64 v[20:21], s[50:51], 0, v[64:65]
	s_mov_b64 s[0:1], 0x1a00000
	v_lshlrev_b32_e32 v66, 3, v138
	v_and_b32_e32 v162, 0x70, v129
	v_mov_b32_e32 v69, v65
	v_mov_b32_e32 v71, v65
	v_lshlrev_b32_e32 v72, 12, v26
	v_mov_b32_e32 v73, v65
	v_lshlrev_b32_e32 v74, 12, v27
	v_mov_b32_e32 v75, v65
	v_lshlrev_b32_e32 v76, 12, v28
	v_mov_b32_e32 v77, v65
	v_lshlrev_b32_e32 v78, 12, v29
	v_mov_b32_e32 v79, v65
	v_lshlrev_b32_e32 v80, 12, v30
	v_mov_b32_e32 v81, v65
	v_lshlrev_b32_e32 v82, 12, v31
	v_mov_b32_e32 v83, v65
	s_addc_u32 s44, s51, 0
	v_lshl_add_u64 v[88:89], v[20:21], 0, s[0:1]
	s_mov_b32 s45, 0xc2fc0000
	s_mov_b32 s46, 0x3f2aaaab
	v_mov_b32_e32 v163, 0x3ecc95a3
	s_mov_b32 s47, 0x3f317218
	s_mov_b32 s52, 0x33800000
	s_mov_b32 s19, 0
	v_lshlrev_b32_e32 v90, 1, v0
	v_lshlrev_b32_e32 v92, 1, v2
	s_mov_b64 s[20:21], 0x40000
	v_add_u32_e32 v164, 0x1000, v129
	s_mov_b64 s[22:23], 0x80000
	v_add_u32_e32 v165, 0x2000, v129
	s_mov_b64 s[24:25], 0xc0000
	v_add_u32_e32 v166, 0x3000, v129
	s_movk_i32 s53, 0x7fff
	v_add_u32_e32 v167, v13, v3
	v_add_u32_e32 v168, v15, v3
	v_add_u32_e32 v169, v17, v3
	v_add_u32_e32 v170, v19, v3
	v_add_u32_e32 v171, v22, v3
	v_add_u32_e32 v172, v23, v3
	v_add_u32_e32 v173, v24, v3
	v_add_u32_e32 v174, v25, v3
	v_add_u32_e32 v175, v7, v9
	v_add_u32_e32 v176, v7, v5
	v_add_u32_e32 v177, v11, v9
	v_add_u32_e32 v178, v11, v5
	s_mov_b32 s54, 0x7060302
	v_lshlrev_b32_e32 v94, 1, v4
	v_lshlrev_b32_e32 v96, 1, v6
	v_lshlrev_b32_e32 v98, 1, v8
	v_lshlrev_b32_e32 v100, 1, v10
	v_lshlrev_b32_e32 v102, 1, v12
	v_lshlrev_b32_e32 v104, 1, v14
	v_lshlrev_b32_e32 v106, 1, v16
	v_lshlrev_b32_e32 v108, 1, v18
	s_mov_b64 s[26:27], 0x4000
	s_mov_b64 s[28:29], 0x8000
	s_mov_b64 s[30:31], 0xc000
	s_mov_b64 s[34:35], 0x10000
	s_movk_i32 s55, 0xf800
	v_mov_b32_e32 v179, 0x42800000
	v_mov_b32_e32 v180, 0x7fc00000
	v_mov_b32_e32 v181, 0xff800000
	s_mov_b32 s61, s2
	v_readfirstlane_b32 s60, v129
	s_branch .Lmy_m1a_map
.LBB0_502:
	s_cmp_lg_u32 s60, 0
	s_cbranch_scc1 .Lmy_m1a_rd
	s_waitcnt vmcnt(8)
	v_readfirstlane_b32 s61, v254
	s_add_i32 s61, s61, s3
	v_mov_b32_e32 v254, s61
	v_mov_b32_e32 v255, 0x10018
	ds_write_b32 v255, v254
	s_waitcnt lgkmcnt(0)
.Lmy_m1a_rd:
	s_barrier
	v_mov_b32_e32 v255, 0x10018
	ds_read_b32 v254, v255
	s_waitcnt lgkmcnt(0)
	v_readfirstlane_b32 s61, v254
.Lmy_m1a_map:
	s_cmpk_lt_i32 s61, 0x800
	s_cbranch_scc0 .LBB0_515
	s_mov_b32 s56, s61
	s_cmpk_ge_i32 s61, 0x400
	s_cbranch_scc1 .Lmy_m1a_go
	s_lshr_b32 s64, s61, 8
	s_sub_i32 s64, 3, s64
	s_and_b32 s65, s61, 0xff
	s_lshr_b32 s66, s65, 7
	s_and_b32 s67, s65, 0x7e
	s_lshl_b32 s67, s67, 2
	s_and_b32 s68, s65, 1
	s_or_b32 s67, s67, s68
	s_sub_i32 s69, 3, s64
	s_cmp_eq_u32 s66, 0
	s_cselect_b32 s70, s64, s69
	s_lshl_b32 s70, s70, 1
	s_or_b32 s67, s67, s70
	s_lshl_b32 s66, s66, 9
	s_or_b32 s56, s67, s66
.Lmy_m1a_go:
	s_cmp_lg_u32 s60, 0
	s_cbranch_scc1 .LBB0_503
	s_mov_b64 s[62:63], exec
	s_mov_b64 exec, 1
	v_mov_b32_e32 v255, 0x3880
	v_mov_b32_e32 v254, 1
	global_atomic_add v254, v255, v254, s[96:97] sc0
	s_mov_b64 exec, s[62:63]
